# attention K/V LDS images re-laid as lane-linear MFMA fragments (conflict-free ds_read_b128), new staging thread map
# speedup vs baseline: 1.0046x; 1.0046x over previous
; DI int lane_id() { int l; asm volatile("v_mbcnt_lo_u32_b32 %0, -1, 0\n\tv_mbcnt_hi_u32_b32 %0, -1, %0" : "=v"(l)); return l; }
; DI void attn_phase(LAS unsigned char* lds, const int wid, const bf16_t* Q, const bf16_t* Kn, const bf16_t* Kr, const bf16_t* Vt, bf16_t* O, int G, int c) {
;     const int lane = lane_id(), tid = wid * 64 + lane, r16 = lane & 15, qd = lane >> 4;
;     for (int it = 0;; ++it) {
;         const long L = (long)it * G + c; if (L >= 2048) break;
;         const int xcd = (int)(L & 7), idx = (int)(L >> 3), bh = (idx >> 5) * 8 + xcd, qb = idx & 31, b = bh >> 3, h = bh & 7;
;         const size_t tok0 = (size_t)b * SEQ;
;         const int q0 = qb * 256 + wid * 32;
;         bf16x8 qf[2][3];
; #pragma unroll
;         for (int qt = 0; qt < 2; ++qt) { const bf16_t* qp = Q + (tok0 + q0 + 16 * qt + r16) * 768 + h * 96 + 8 * qd;
; #pragma unroll
;           for (int ks = 0; ks < 3; ++ks) qf[qt][ks] = *(const bf16x8*)(qp + 32 * ks); }
;         f32x4 oacc[4][2], sa[4][2], sb[4][2];
;         f32x4 negm0 = {0.f, 0.f, 0.f, 0.f}, negm1 = {0.f, 0.f, 0.f, 0.f};
; #pragma unroll
;         for (int t4 = 0; t4 < 4; ++t4) { oacc[t4][0] = (f32x4){0.f, 0.f, 0.f, 0.f}; oacc[t4][1] = (f32x4){0.f, 0.f, 0.f, 0.f}; }
;         float l0 = 0.f, l1 = 0.f;
;         const int skey = tid >> 3, sch = tid & 7;
;         const int rkey = (tid & 255) >> 2, rch = tid & 3;
;         const bf16_t* gkn = Kn + (tok0 + skey) * 512 + h * 64 + sch * 8;
;         const bf16_t* gkr = Kr + (tok0 + rkey) * 32 + rch * 8;
;         const bf16_t* gvt = Vt + (size_t)(h * 64 + skey) * T + tok0 + sch * 8;
;         const unsigned lkn = skey * KS_STRIDE + sch * 16, lkr = rkey * KS_STRIDE + 128 + rch * 16, lvt = VOFF + skey * VS_STRIDE + (sch >> 2) * 64 + ((sch & 1) * 4 + ((sch >> 1) & 1)) * 8;
.LBB0_856:
	s_mov_b64 s[6:7], s[0:1]
	s_mov_b64 s[8:9], s[0:1]
	s_load_dwordx2 s[6:7], s[6:7], 0xf8
	s_mov_b64 s[10:11], s[0:1]
	s_load_dwordx2 s[8:9], s[8:9], 0xf8
	s_load_dwordx2 s[14:15], s[10:11], 0xf8
	s_mov_b64 s[10:11], s[0:1]
	s_load_dwordx2 s[28:29], s[10:11], 0xf8
	s_mov_b64 s[10:11], s[0:1]
	s_load_dwordx2 s[16:17], s[10:11], 0xf8
	v_mbcnt_lo_u32_b32 v1, -1, 0
	v_mbcnt_hi_u32_b32 v1, -1, v1
	v_mov_b32_e32 v0, 0
	v_ashrrev_i32_e32 v9, 4, v1
	v_lshlrev_b32_e32 v2, 3, v9
	v_ashrrev_i32_e32 v3, 31, v2
	s_waitcnt lgkmcnt(0)
	v_lshl_add_u64 v[2:3], v[2:3], 1, s[6:7]
	s_mov_b64 s[6:7], 0x26cc0000
	v_lshlrev_b32_e32 v4, 4, v1
	v_add_u32_e32 v8, s33, v1
	v_lshl_add_u64 v[158:159], v[2:3], 0, s[6:7]
	v_lshrrev_b32_e32 v3, 3, v1
	v_and_b32_e32 v4, 48, v1
	v_mov_b32_e32 v5, v0
	v_lshrrev_b32_e32 v236, 6, v8
	v_and_b32_e32 v237, 7, v1
	v_and_b32_e32 v238, 15, v1
	v_lshl_or_b32 v160, v236, 3, v237
	v_mul_u32_u24_e32 v243, 0xc00, v236
	v_lshlrev_b32_e32 v244, 4, v1
	v_lshrrev_b32_e32 v239, 4, v160
	v_and_b32_e32 v240, 15, v160
	v_lshlrev_b32_e32 v241, 11, v239
	v_mul_u32_u24_e32 v239, 0xc00, v239
	v_lshlrev_b32_e32 v240, 4, v240
	v_lshl_add_u32 v239, v3, 8, v239
	v_bfe_u32 v242, v3, 2, 1
	v_add_u32_e32 v239, v239, v240
	v_lshl_or_b32 v241, v242, 10, v241
	v_and_b32_e32 v242, 1, v3
	v_or_b32_e32 v241, v241, v240
	v_lshl_or_b32 v241, v242, 9, v241
	v_bfe_u32 v242, v3, 1, 1
	v_add_u32_e32 v243, v243, v244
	v_lshl_or_b32 v241, v242, 3, v241
	v_add_u32_e32 v243, 0x800, v243
	v_lshl_add_u64 v[6:7], s[14:15], 0, v[4:5]
	s_mov_b64 s[6:7], 0x208c0000
	v_lshlrev_b32_e32 v166, 4, v3
	s_movk_i32 s21, 0xd0
	v_lshl_add_u64 v[164:165], v[6:7], 0, s[6:7]
	s_movk_i32 s6, 0x90
	v_lshlrev_b32_e32 v2, 3, v3
	s_movk_i32 s6, 0x100
	v_cmp_gt_i32_e64 s[10:11], s6, v8
	s_movk_i32 s6, 0xff
	s_add_u32 s30, s8, 0x2ccc0000
	v_lshl_or_b32 v162, v236, 4, v238
	v_and_b32_e32 v162, 63, v162
	v_cmp_lt_i32_e64 s[12:13], s6, v8
	v_lshlrev_b32_e32 v8, 2, v9
	s_addc_u32 s31, s9, 0
	v_ashrrev_i32_e32 v9, 31, v8
	s_load_dword s68, s[0:1], 0x108
	s_add_u32 s34, s28, 0x338c0000
	v_and_b32_e32 v156, 15, v1
	v_lshl_add_u64 v[8:9], v[8:9], 1, s[16:17]
	s_mov_b64 s[6:7], 0x3b8c0000
	v_lshl_or_b32 v4, v162, 6, v4
	v_mov_b32_e32 v5, v0
	s_addc_u32 s35, s29, 0
	s_ashr_i32 s33, s18, 31
	v_ashrrev_i32_e32 v161, 31, v160
	v_lshl_add_u64 v[168:169], v[8:9], 0, s[6:7]
	v_lshl_add_u64 v[4:5], s[14:15], 0, v[4:5]
	s_mov_b64 s[6:7], 0x208c6000
	s_mov_b32 s73, s5
	s_cmpk_gt_u32 s5, 0xff
	v_lshl_add_u64 v[170:171], v[4:5], 0, s[6:7]
	v_lshlrev_b64 v[4:5], 10, v[160:161]
	s_mov_b32 s69, s4
	v_readlane_b32 s4, v255, 12
	v_readlane_b32 s70, v255, 4
	v_readlane_b32 s54, v255, 6
	s_mov_b32 s64, s18
	s_mov_b32 s37, 0
	s_cselect_b64 s[38:39], -1, 0
	v_mov_b32_e32 v167, v0
	v_lshl_add_u64 v[172:173], s[8:9], 0, v[4:5]
	v_mov_b64_e32 v[174:175], 0x7ff
	s_movk_i32 s6, 0x600
	s_mov_b64 s[40:41], 0x6000
	s_movk_i32 s7, 0x6000
	v_lshlrev_b32_e32 v176, 1, v2
	s_mov_b32 s8, 0x40c00000
	s_mov_b64 s[42:43], 0x100
	s_mov_b64 s[44:45], 0x2000
	s_mov_b64 s[46:47], 0x20000
	v_mov_b32_e32 v196, 0x600
	v_mov_b32_e32 v197, v239
	v_mov_b32_e32 v198, v241
	v_mov_b32_e32 v199, v243
	v_mov_b32_e32 v200, v244
	s_mov_b32 s9, s2
	s_mov_b32 s21, 0
	v_readlane_b32 s5, v255, 13
	v_readlane_b32 s71, v255, 5
	v_readlane_b32 s55, v255, 7
	s_branch .LBB0_859

; DI void attn_phase(LAS unsigned char* lds, const int wid, const bf16_t* Q, const bf16_t* Kn, const bf16_t* Kr, const bf16_t* Vt, bf16_t* O, int G, int c) {
;     ...
;         const long L = (long)it * G + c; if (L >= 2048) break;
;         const int xcd = (int)(L & 7), idx = (int)(L >> 3), bh = (idx >> 5) * 8 + xcd, qb = idx & 31, b = bh >> 3, h = bh & 7;
;         const size_t tok0 = (size_t)b * SEQ;
;         const int q0 = qb * 256 + wid * 32;
;         bf16x8 qf[2][3];
; #pragma unroll
;         for (int qt = 0; qt < 2; ++qt) { const bf16_t* qp = Q + (tok0 + q0 + 16 * qt + r16) * 768 + h * 96 + 8 * qd;
; #pragma unroll
;           for (int ks = 0; ks < 3; ++ks) qf[qt][ks] = *(const bf16x8*)(qp + 32 * ks); }
;         f32x4 oacc[4][2], sa[4][2], sb[4][2];
;         f32x4 negm0 = {0.f, 0.f, 0.f, 0.f}, negm1 = {0.f, 0.f, 0.f, 0.f};
; #pragma unroll
;         for (int t4 = 0; t4 < 4; ++t4) { oacc[t4][0] = (f32x4){0.f, 0.f, 0.f, 0.f}; oacc[t4][1] = (f32x4){0.f, 0.f, 0.f, 0.f}; }
;         float l0 = 0.f, l1 = 0.f;
;         const int skey = tid >> 3, sch = tid & 7;
;         const int rkey = (tid & 255) >> 2, rch = tid & 3;
;         const bf16_t* gkn = Kn + (tok0 + skey) * 512 + h * 64 + sch * 8;
;         const bf16_t* gkr = Kr + (tok0 + rkey) * 32 + rch * 8;
;         const bf16_t* gvt = Vt + (size_t)(h * 64 + skey) * T + tok0 + sch * 8;
;         const unsigned lkn = skey * KS_STRIDE + sch * 16, lkr = rkey * KS_STRIDE + 128 + rch * 16, lvt = VOFF + skey * VS_STRIDE + (sch >> 2) * 64 + ((sch & 1) * 4 + ((sch >> 1) & 1)) * 8;
;         u32x4 rkn = *(const u32x4*)gkn, rvt = *(const u32x4*)gvt, rkr = {0u, 0u, 0u, 0u};
;         if (tid < 256) rkr = *(const u32x4*)gkr;
;         *(LAS u32x4*)(lds + lkn) = rkn; *(LAS u32x2*)(lds + lvt) = (u32x2){rvt.x, rvt.y}; *(LAS u32x2*)(lds + lvt + 16) = (u32x2){rvt.z, rvt.w}; if (tid < 256) *(LAS u32x4*)(lds + lkr) = rkr;
;         rkn = *(const u32x4*)(gkn + 64 * 512); if (tid < 256) rkr = *(const u32x4*)(gkr + 64 * 32);
;         *(LAS u32x4*)(lds + KS_BYTES + lkn) = rkn; if (tid < 256) *(LAS u32x4*)(lds + KS_BYTES + lkr) = rkr;
;         __syncthreads();
;         { const LAS unsigned char* kp = lds + r16 * KS_STRIDE + qd * 16;
; #pragma unroll
;           for (int t4 = 0; t4 < 4; ++t4) { sa[t4][0] = negm0; sa[t4][1] = negm1; }
; #pragma unroll
;           for (int ks = 0; ks < 3; ++ks)
; #pragma unroll
.LBB0_859:
	s_mul_i32 s14, s21, s33
	s_mul_hi_u32 s15, s21, s64
	s_add_i32 s15, s15, s14
	s_mul_i32 s14, s21, s64
	s_add_u32 s16, s14, s2
	s_addc_u32 s17, s15, s3
	v_cmp_gt_i64_e32 vcc, s[16:17], v[174:175]
	s_mov_b64 s[14:15], -1
	s_cbranch_vccnz .LBB0_858
	s_and_b32 s26, s16, 7
	s_lshr_b64 s[16:17], s[16:17], 3
	s_ashr_i32 s14, s16, 5
	s_lshl_b32 s16, s16, 8
	s_ashr_i32 s15, s14, 31
	s_and_b32 s16, s16, 0x1f00
	s_lshl_b64 s[48:49], s[14:15], 13
	s_add_i32 s16, s16, s24
	s_add_u32 s16, s48, s16
	s_mul_i32 s36, s26, 0xc0
	v_or_b32_e32 v178, s16, v156
	v_lshl_add_u64 v[2:3], v[158:159], 0, s[36:37]
	s_addc_u32 s27, s49, 0
	v_mad_u64_u32 v[2:3], s[16:17], v178, s6, v[2:3]
	v_mad_i32_i24 v3, s27, v196, v3
	v_add_co_u32_e32 v16, vcc, s7, v2
	v_lshl_add_u64 v[24:25], v[2:3], 0, s[40:41]
	s_nop 0
	v_addc_co_u32_e32 v17, vcc, 0, v3, vcc
	global_load_dwordx4 v[4:7], v[2:3], off offset:64
	global_load_dwordx4 v[8:11], v[2:3], off offset:128
	global_load_dwordx4 v[12:15], v[2:3], off
	s_nop 0
	global_load_dwordx4 v[16:19], v[16:17], off
	s_nop 0
	global_load_dwordx4 v[20:23], v[24:25], off offset:64
	s_nop 0
	global_load_dwordx4 v[24:27], v[24:25], off offset:128
	v_lshl_add_u64 v[2:3], s[48:49], 0, v[160:161]
	v_lshlrev_b64 v[2:3], 10, v[2:3]
	v_lshl_add_u64 v[2:3], s[30:31], 0, v[2:3]
	s_lshl_b32 s36, s26, 7
	s_lshl_b32 s25, s26, 6
	v_lshl_add_u64 v[2:3], v[2:3], 0, s[36:37]
	v_mov_b32_e32 v177, v0
	v_lshl_add_u64 v[154:155], v[2:3], 0, v[176:177]
	v_add_u32_e32 v2, s25, v160
	v_ashrrev_i32_e32 v3, 31, v2
	v_lshlrev_b64 v[2:3], 17, v[2:3]
	v_lshl_add_u64 v[2:3], s[34:35], 0, v[2:3]
	s_lshl_b64 s[16:17], s[14:15], 14
	v_lshl_add_u64 v[2:3], v[2:3], 0, s[16:17]
	v_lshl_add_u64 v[152:153], v[2:3], 0, v[176:177]
	global_load_dwordx4 v[32:35], v[154:155], off
	global_load_dwordx4 v[28:31], v[152:153], off
	v_mov_b32_e32 v179, s27
	v_add_u32_e32 v177, 0x6000, v198
	s_and_saveexec_b64 s[26:27], s[12:13]
	s_xor_b64 s[50:51], exec, s[26:27]
	s_cbranch_execz .LBB0_862
	s_waitcnt vmcnt(1)
	ds_write_b128 v197, v[32:35]
	s_waitcnt vmcnt(0)
	ds_write2_b64 v177, v[28:29], v[30:31] offset1:32
.LBB0_862:
	s_or_saveexec_b64 s[50:51], s[50:51]
	v_mov_b32_e32 v3, s49
	v_or_b32_e32 v2, s48, v162
	v_lshlrev_b64 v[2:3], 6, v[2:3]
	v_lshl_add_u64 v[180:181], v[164:165], 0, v[2:3]
	s_xor_b64 exec, exec, s[50:51]
	s_cbranch_execz .LBB0_864
	global_load_dwordx4 v[36:39], v[180:181], off
	s_waitcnt vmcnt(2)
	ds_write_b128 v197, v[32:35]
	s_waitcnt vmcnt(1)
	ds_write2_b64 v177, v[28:29], v[30:31] offset1:32
	s_waitcnt vmcnt(0)
	ds_write_b128 v199, v[36:39]
.LBB0_864:
	s_or_b64 exec, exec, s[50:51]
	v_add_co_u32_e32 v2, vcc, 0x10000, v154
	s_nop 1
	v_addc_co_u32_e32 v3, vcc, 0, v155, vcc
	global_load_dwordx4 v[28:31], v[2:3], off
	s_and_saveexec_b64 s[26:27], s[12:13]
	s_xor_b64 s[48:49], exec, s[26:27]
	s_cbranch_execz .LBB0_866
	s_waitcnt vmcnt(0)
	ds_write_b128 v197, v[28:31] offset:12288
.LBB0_866:
	s_andn2_saveexec_b64 s[48:49], s[48:49]
	s_cbranch_execz .LBB0_868
	v_add_co_u32_e32 v2, vcc, 0x1000, v180
	s_nop 1
	v_addc_co_u32_e32 v3, vcc, 0, v181, vcc
	global_load_dwordx4 v[32:35], v[2:3], off
	s_waitcnt vmcnt(1)
	ds_write_b128 v197, v[28:31] offset:12288
	s_waitcnt vmcnt(0)
	ds_write_b128 v199, v[32:35] offset:12288
.LBB0_868:
	s_or_b64 exec, exec, s[48:49]
	v_mov_b32_e32 v201, v200
	s_waitcnt lgkmcnt(0)
	s_barrier
	s_waitcnt vmcnt(0)
	ds_read_b128 v[28:31], v201
	ds_read_b128 v[32:35], v201 offset:1024
	s_waitcnt lgkmcnt(1)
	v_mfma_f32_16x16x32_bf16 v[36:39], v[28:31], v[12:15], 0
	ds_read_b128 v[40:43], v201 offset:3072
	ds_read_b128 v[44:47], v201 offset:2048
	ds_read_b128 v[52:55], v201 offset:6144
	ds_read_b128 v[56:59], v201 offset:7168
	ds_read_b128 v[64:67], v201 offset:9216
	ds_read_b128 v[72:75], v201 offset:8192
	v_mfma_f32_16x16x32_bf16 v[28:31], v[28:31], v[16:19], 0
	v_add_co_u32_e32 v2, vcc, 0x20000, v154
	v_mov_b32_e32 v1, v0
	s_waitcnt lgkmcnt(5)
	v_mfma_f32_16x16x32_bf16 v[48:51], v[40:43], v[12:15], 0
	v_addc_co_u32_e32 v3, vcc, 0, v155, vcc
	v_mfma_f32_16x16x32_bf16 v[40:43], v[40:43], v[16:19], 0
	s_waitcnt lgkmcnt(3)
	v_mfma_f32_16x16x32_bf16 v[60:63], v[52:55], v[12:15], 0
	v_mfma_f32_16x16x32_bf16 v[52:55], v[52:55], v[16:19], 0
	v_mfma_f32_16x16x32_bf16 v[36:39], v[32:35], v[4:7], v[36:39]
	v_mfma_f32_16x16x32_bf16 v[28:31], v[32:35], v[20:23], v[28:31]
	ds_read_b128 v[32:35], v201 offset:4096
	ds_read_b128 v[76:79], v201 offset:5120
	s_waitcnt lgkmcnt(3)
	v_mfma_f32_16x16x32_bf16 v[68:71], v[64:67], v[12:15], 0
	v_mfma_f32_16x16x32_bf16 v[64:67], v[64:67], v[16:19], 0
	s_waitcnt lgkmcnt(1)
	v_mfma_f32_16x16x32_bf16 v[48:51], v[32:35], v[4:7], v[48:51]
	v_mfma_f32_16x16x32_bf16 v[32:35], v[32:35], v[20:23], v[40:43]
	v_mfma_f32_16x16x32_bf16 v[40:43], v[56:59], v[4:7], v[60:63]
	v_mfma_f32_16x16x32_bf16 v[52:55], v[56:59], v[20:23], v[52:55]
	ds_read_b128 v[56:59], v201 offset:10240
	ds_read_b128 v[98:101], v201 offset:11264
	s_waitcnt lgkmcnt(0)
	s_barrier
	v_mfma_f32_16x16x32_bf16 v[60:63], v[56:59], v[4:7], v[68:71]
	v_mfma_f32_16x16x32_bf16 v[64:67], v[56:59], v[20:23], v[64:67]
	v_mfma_f32_16x16x32_bf16 v[80:83], v[76:79], v[8:11], v[48:51]
	v_mfma_f32_16x16x32_bf16 v[84:87], v[76:79], v[24:27], v[32:35]
	v_mfma_f32_16x16x32_bf16 v[76:79], v[72:75], v[24:27], v[52:55]
	global_load_dwordx4 v[56:59], v[2:3], off
	s_nop 1
	global_load_dwordx4 v[52:55], v[152:153], off offset:128
	v_mov_b32_e32 v2, v0
	v_mov_b32_e32 v3, v0
	v_mfma_f32_16x16x32_bf16 v[88:91], v[44:47], v[8:11], v[36:39]
	v_mfma_f32_16x16x32_bf16 v[94:97], v[44:47], v[24:27], v[28:31]
	v_mfma_f32_16x16x32_bf16 v[68:71], v[72:75], v[8:11], v[40:43]
	s_nop 1
	v_mov_b64_e32 v[30:31], v[2:3]
	v_mov_b64_e32 v[28:29], v[0:1]
	v_mfma_f32_16x16x32_bf16 v[60:63], v[98:101], v[8:11], v[60:63]
	v_mfma_f32_16x16x32_bf16 v[64:67], v[98:101], v[24:27], v[64:67]
	s_and_saveexec_b64 s[48:49], s[10:11]
	s_cbranch_execz .LBB0_870
	v_add_co_u32_e32 v2, vcc, 0x2000, v180
	s_nop 1
	v_addc_co_u32_e32 v3, vcc, 0, v181, vcc
	global_load_dwordx4 v[28:31], v[2:3], off

.LBB0_877:
	ds_read_b128 v[72:75], v201 offset:12288
	ds_read_b128 v[98:101], v201 offset:13312
	ds_read_b128 v[106:109], v201 offset:15360
	ds_read_b128 v[110:113], v201 offset:14336
	ds_read_b128 v[128:131], v201 offset:18432
	ds_read_b128 v[132:135], v201 offset:19456
	ds_read_b128 v[140:143], v201 offset:21504
	ds_read_b128 v[144:147], v201 offset:20480
	s_waitcnt lgkmcnt(7)
	v_mfma_f32_16x16x32_bf16 v[102:105], v[72:75], v[12:15], v[44:47]
	v_exp_f32_e32 v91, v91
	v_exp_f32_e32 v83, v83
	v_exp_f32_e32 v69, v69
	v_mfma_f32_16x16x32_bf16 v[72:75], v[72:75], v[16:19], v[48:51]
	v_exp_f32_e32 v71, v71
	v_exp_f32_e32 v63, v63
	s_waitcnt lgkmcnt(5)
	v_mfma_f32_16x16x32_bf16 v[114:117], v[106:109], v[12:15], v[44:47]
	v_mfma_f32_16x16x32_bf16 v[106:109], v[106:109], v[16:19], v[48:51]
	s_waitcnt lgkmcnt(3)
	v_mfma_f32_16x16x32_bf16 v[136:139], v[128:131], v[12:15], v[44:47]
	v_mfma_f32_16x16x32_bf16 v[128:131], v[128:131], v[16:19], v[48:51]
	v_mfma_f32_16x16x32_bf16 v[102:105], v[98:101], v[4:7], v[102:105]
	v_mfma_f32_16x16x32_bf16 v[98:101], v[98:101], v[20:23], v[72:75]
	s_nop 2
	ds_read_b128 v[72:75], v201 offset:16384
	ds_read_b128 v[182:185], v201 offset:17408
	s_waitcnt lgkmcnt(3)
	v_mfma_f32_16x16x32_bf16 v[148:151], v[140:143], v[12:15], v[44:47]
	v_mfma_f32_16x16x32_bf16 v[140:143], v[140:143], v[16:19], v[48:51]
	s_waitcnt lgkmcnt(1)
	v_mfma_f32_16x16x32_bf16 v[186:189], v[72:75], v[4:7], v[114:117]
	v_mfma_f32_16x16x32_bf16 v[190:193], v[72:75], v[20:23], v[106:109]
	v_mfma_f32_16x16x32_bf16 v[136:139], v[132:135], v[4:7], v[136:139]
	v_mfma_f32_16x16x32_bf16 v[128:131], v[132:135], v[20:23], v[128:131]
	ds_read_b128 v[72:75], v201 offset:22528
	ds_read_b128 v[132:135], v201 offset:23552
	s_waitcnt lgkmcnt(1)
	v_mfma_f32_16x16x32_bf16 v[140:143], v[72:75], v[20:23], v[140:143]
	v_mfma_f32_16x16x32_bf16 v[148:151], v[72:75], v[4:7], v[148:151]
	v_mfma_f32_16x16x32_bf16 v[72:75], v[110:113], v[8:11], v[102:105]
	v_mfma_f32_16x16x32_bf16 v[116:119], v[110:113], v[24:27], v[98:101]
	v_mfma_f32_16x16x32_bf16 v[108:111], v[182:185], v[8:11], v[186:189]
	v_mfma_f32_16x16x32_bf16 v[112:115], v[182:185], v[24:27], v[190:193]
	v_exp_f32_e32 v183, v88
	v_exp_f32_e32 v182, v94
	v_exp_f32_e32 v185, v89
	v_exp_f32_e32 v184, v95
	v_exp_f32_e32 v89, v90
	v_exp_f32_e32 v88, v96
	v_exp_f32_e32 v90, v97
	v_exp_f32_e32 v187, v80
	v_exp_f32_e32 v186, v84
	v_exp_f32_e32 v189, v81
	v_exp_f32_e32 v188, v85
	v_exp_f32_e32 v81, v82
	v_exp_f32_e32 v80, v86
	v_exp_f32_e32 v82, v87
	v_mfma_f32_16x16x32_bf16 v[100:103], v[144:147], v[8:11], v[136:139]
	v_exp_f32_e32 v85, v68
	v_exp_f32_e32 v84, v76
	v_exp_f32_e32 v68, v77
	v_mfma_f32_16x16x32_bf16 v[104:107], v[144:147], v[24:27], v[128:131]
	v_cvt_pk_bf16_f32 v136, v182, v184
	v_cvt_pk_bf16_f32 v137, v88, v90
	v_cvt_pk_bf16_f32 v138, v186, v188
	s_waitcnt lgkmcnt(0)
	v_mfma_f32_16x16x32_bf16 v[96:99], v[132:135], v[24:27], v[140:143]
	ds_read_b128 v[128:131], v200 offset:24576
	s_nop 1
	ds_read_b128 v[140:143], v200 offset:26624
	ds_read_b128 v[144:147], v200 offset:25600
	v_cvt_pk_bf16_f32 v139, v80, v82
	v_mfma_f32_16x16x32_bf16 v[92:95], v[132:135], v[8:11], v[148:151]
	v_cvt_pk_bf16_f32 v132, v183, v185
	v_cvt_pk_bf16_f32 v133, v89, v91
	v_cvt_pk_bf16_f32 v134, v187, v189
	v_cvt_pk_bf16_f32 v135, v81, v83
	ds_read_b128 v[190:193], v200 offset:28672
	ds_read_b128 v[204:207], v200 offset:27648
	s_waitcnt lgkmcnt(3)
	v_mfma_f32_16x16x32_bf16 v[208:211], v[140:143], v[132:135], v[124:127]
	v_exp_f32_e32 v77, v70
	v_exp_f32_e32 v76, v78
	v_exp_f32_e32 v70, v79
	v_mfma_f32_16x16x32_bf16 v[212:215], v[140:143], v[136:139], v[120:123]
	ds_read_b128 v[140:143], v200 offset:30720
	ds_read_b128 v[216:219], v200 offset:29696
	ds_read_b128 v[224:227], v200 offset:31744
	v_exp_f32_e32 v79, v60
	v_exp_f32_e32 v78, v64
	v_exp_f32_e32 v87, v61
	v_exp_f32_e32 v86, v65
	v_exp_f32_e32 v61, v62
	v_exp_f32_e32 v60, v66
	v_exp_f32_e32 v62, v67
	v_mfma_f32_16x16x32_bf16 v[148:151], v[128:131], v[132:135], v[124:127]
	v_cvt_pk_bf16_f32 v228, v84, v68
	v_cvt_pk_bf16_f32 v229, v76, v70
	v_cvt_pk_bf16_f32 v230, v78, v86
	v_mfma_f32_16x16x32_bf16 v[128:131], v[128:131], v[136:139], v[120:123]
	v_cvt_pk_bf16_f32 v231, v60, v62
	s_waitcnt vmcnt(3)
	ds_write_b128 v197, v[56:59]
	s_waitcnt lgkmcnt(5)
	v_mfma_f32_16x16x32_bf16 v[220:223], v[190:193], v[132:135], v[124:127]
	v_mfma_f32_16x16x32_bf16 v[190:193], v[190:193], v[136:139], v[120:123]
	s_waitcnt lgkmcnt(3)
	v_mfma_f32_16x16x32_bf16 v[124:127], v[140:143], v[132:135], v[124:127]
	v_mfma_f32_16x16x32_bf16 v[64:67], v[140:143], v[136:139], v[120:123]
	s_nop 2
	v_cvt_pk_bf16_f32 v120, v85, v69
	v_cvt_pk_bf16_f32 v121, v77, v71
	v_cvt_pk_bf16_f32 v122, v79, v87
	v_cvt_pk_bf16_f32 v123, v61, v63
	v_mfma_f32_16x16x32_bf16 v[136:139], v[204:207], v[228:231], v[212:215]
	s_nop 0
	v_mfma_f32_16x16x32_bf16 v[148:151], v[144:147], v[120:123], v[148:151]
	v_mfma_f32_16x16x32_bf16 v[144:147], v[144:147], v[228:231], v[128:131]
	v_mfma_f32_16x16x32_bf16 v[140:143], v[204:207], v[120:123], v[208:211]
	s_waitcnt lgkmcnt(2)
	v_mfma_f32_16x16x32_bf16 v[132:135], v[216:219], v[120:123], v[220:223]
	v_mfma_f32_16x16x32_bf16 v[128:131], v[216:219], v[228:231], v[190:193]
	s_waitcnt lgkmcnt(1)
	v_mfma_f32_16x16x32_bf16 v[124:127], v[224:227], v[120:123], v[124:127]
	v_mfma_f32_16x16x32_bf16 v[120:123], v[224:227], v[228:231], v[64:67]
	s_and_saveexec_b64 s[48:49], s[10:11]
	s_cbranch_execz .LBB0_879
	s_waitcnt vmcnt(2)
	ds_write_b128 v199, v[28:31]
.LBB0_879:
	s_or_b64 exec, exec, s[48:49]
	v_add_u32_e32 v1, 0x8000, v198
	s_waitcnt vmcnt(2)
	ds_write2_b64 v1, v[52:53], v[54:55] offset1:32
	v_add_co_u32_e32 v52, vcc, 0x40000, v154
	s_waitcnt lgkmcnt(0)
	s_nop 0
	v_addc_co_u32_e32 v53, vcc, 0, v155, vcc
	s_barrier
	global_load_dwordx4 v[52:55], v[52:53], off
	s_and_saveexec_b64 s[48:49], s[10:11]
	s_cbranch_execz .LBB0_881
	v_add_co_u32_e32 v28, vcc, 0x4000, v180
	s_nop 1
	v_addc_co_u32_e32 v29, vcc, 0, v181, vcc
	global_load_dwordx4 v[28:31], v[28:29], off

.LBB0_883:
	ds_read_b128 v[60:63], v201
	ds_read_b128 v[64:67], v201 offset:1024
	ds_read_b128 v[76:79], v201 offset:3072
	ds_read_b128 v[80:83], v201 offset:2048
	ds_read_b128 v[88:91], v201 offset:6144
	ds_read_b128 v[152:155], v201 offset:7168
	ds_read_b128 v[184:187], v201 offset:9216
	ds_read_b128 v[188:191], v201 offset:8192
	s_waitcnt lgkmcnt(7)
	v_mfma_f32_16x16x32_bf16 v[68:71], v[60:63], v[12:15], v[44:47]
	v_mfma_f32_16x16x32_bf16 v[60:63], v[60:63], v[16:19], v[48:51]
	s_waitcnt lgkmcnt(5)
	v_mfma_f32_16x16x32_bf16 v[84:87], v[76:79], v[12:15], v[44:47]
	v_mfma_f32_16x16x32_bf16 v[76:79], v[76:79], v[16:19], v[48:51]
	v_mfma_f32_16x16x32_bf16 v[68:71], v[64:67], v[4:7], v[68:71]
	v_mfma_f32_16x16x32_bf16 v[60:63], v[64:67], v[20:23], v[60:63]
	ds_read_b128 v[64:67], v201 offset:4096
	ds_read_b128 v[204:207], v201 offset:5120
	s_waitcnt lgkmcnt(5)
	v_mfma_f32_16x16x32_bf16 v[180:183], v[88:91], v[12:15], v[44:47]
	v_mfma_f32_16x16x32_bf16 v[88:91], v[88:91], v[16:19], v[48:51]
	s_waitcnt lgkmcnt(3)
	v_mfma_f32_16x16x32_bf16 v[192:195], v[184:187], v[12:15], v[44:47]
	s_waitcnt lgkmcnt(1)
	v_mfma_f32_16x16x32_bf16 v[208:211], v[64:67], v[4:7], v[84:87]
	v_mfma_f32_16x16x32_bf16 v[64:67], v[64:67], v[20:23], v[76:79]
	s_nop 2
	ds_read_b128 v[76:79], v201 offset:10240
	ds_read_b128 v[216:219], v201 offset:11264
	v_mfma_f32_16x16x32_bf16 v[184:187], v[184:187], v[16:19], v[48:51]
	v_mfma_f32_16x16x32_bf16 v[180:183], v[152:155], v[4:7], v[180:183]
	v_mfma_f32_16x16x32_bf16 v[212:215], v[152:155], v[20:23], v[88:91]
	v_exp_f32_e32 v153, v72
	v_exp_f32_e32 v152, v116
	v_exp_f32_e32 v155, v73
	s_waitcnt lgkmcnt(1)
	v_mfma_f32_16x16x32_bf16 v[192:195], v[76:79], v[4:7], v[192:195]
	v_exp_f32_e32 v154, v117
	s_nop 0
	v_cvt_pk_bf16_f32 v116, v152, v154
	v_mfma_f32_16x16x32_bf16 v[220:223], v[76:79], v[20:23], v[184:187]
	v_mfma_f32_16x16x32_bf16 v[84:87], v[80:83], v[8:11], v[68:71]
	s_nop 1
	v_exp_f32_e32 v187, v111
	v_exp_f32_e32 v185, v75
	v_exp_f32_e32 v184, v119
	v_mfma_f32_16x16x32_bf16 v[88:91], v[80:83], v[24:27], v[60:63]
	v_exp_f32_e32 v186, v115
	v_mfma_f32_16x16x32_bf16 v[80:83], v[204:207], v[24:27], v[64:67]
	v_mfma_f32_16x16x32_bf16 v[60:63], v[188:191], v[8:11], v[180:183]
	v_mfma_f32_16x16x32_bf16 v[68:71], v[188:191], v[24:27], v[212:215]
	v_exp_f32_e32 v191, v109
	v_exp_f32_e32 v189, v110
	v_exp_f32_e32 v181, v74
	s_waitcnt lgkmcnt(0)
	v_mfma_f32_16x16x32_bf16 v[64:67], v[216:219], v[8:11], v[192:195]
	v_exp_f32_e32 v180, v118
	v_exp_f32_e32 v190, v113
	v_exp_f32_e32 v188, v114
	v_exp_f32_e32 v193, v108
	ds_read_b128 v[108:111], v200 offset:32768
	v_exp_f32_e32 v192, v112
	v_mfma_f32_16x16x32_bf16 v[76:79], v[204:207], v[8:11], v[208:211]
	ds_read_b128 v[204:207], v200 offset:34816
	s_nop 1
	ds_read_b128 v[208:211], v200 offset:33792
	v_cvt_pk_bf16_f32 v112, v153, v155
	v_cvt_pk_bf16_f32 v113, v181, v185
	v_cvt_pk_bf16_f32 v114, v193, v191
	v_cvt_pk_bf16_f32 v115, v189, v187
	v_cvt_pk_bf16_f32 v117, v180, v184
	v_cvt_pk_bf16_f32 v118, v192, v190
	v_cvt_pk_bf16_f32 v119, v188, v186
	v_mfma_f32_16x16x32_bf16 v[72:75], v[216:219], v[24:27], v[220:223]
	v_exp_f32_e32 v183, v100
	v_exp_f32_e32 v182, v104
	v_exp_f32_e32 v195, v101
	s_waitcnt lgkmcnt(2)
	v_mfma_f32_16x16x32_bf16 v[148:151], v[108:111], v[112:115], v[148:151]
	v_exp_f32_e32 v194, v105
	v_cvt_pk_bf16_f32 v228, v183, v195
	v_mfma_f32_16x16x32_bf16 v[108:111], v[108:111], v[116:119], v[144:147]
	s_nop 2
	ds_read_b128 v[144:147], v200 offset:36864
	ds_read_b128 v[212:215], v200 offset:35840
	v_cvt_pk_bf16_f32 v232, v182, v194
	s_waitcnt lgkmcnt(3)
	v_mfma_f32_16x16x32_bf16 v[216:219], v[204:207], v[112:115], v[140:143]
	s_nop 2
	v_exp_f32_e32 v141, v102
	v_exp_f32_e32 v140, v106
	v_exp_f32_e32 v143, v103
	v_mfma_f32_16x16x32_bf16 v[100:103], v[204:207], v[116:119], v[136:139]
	v_exp_f32_e32 v142, v107
	ds_read_b128 v[104:107], v200 offset:38912
	s_nop 0
	ds_read_b128 v[136:139], v200 offset:37888
	ds_read_b128 v[220:223], v200 offset:39936
	s_waitcnt lgkmcnt(4)
	v_mfma_f32_16x16x32_bf16 v[204:207], v[144:147], v[112:115], v[132:135]
	v_cvt_pk_bf16_f32 v229, v141, v143
	v_cvt_pk_bf16_f32 v233, v140, v142
	s_waitcnt vmcnt(3)
	ds_write_b128 v197, v[32:35] offset:12288
	v_exp_f32_e32 v133, v92
	v_exp_f32_e32 v132, v96
	v_exp_f32_e32 v135, v93
	v_mfma_f32_16x16x32_bf16 v[144:147], v[144:147], v[116:119], v[128:131]
	v_exp_f32_e32 v134, v97
	v_cvt_pk_bf16_f32 v230, v133, v135
	s_nop 0
	v_exp_f32_e32 v129, v94
	s_waitcnt lgkmcnt(3)
	v_mfma_f32_16x16x32_bf16 v[224:227], v[104:107], v[112:115], v[124:127]
	v_exp_f32_e32 v128, v98
	v_cvt_pk_bf16_f32 v234, v132, v134
	s_nop 0
	v_exp_f32_e32 v125, v95
	v_exp_f32_e32 v124, v99
	v_mfma_f32_16x16x32_bf16 v[92:95], v[104:107], v[116:119], v[120:123]
	v_cvt_pk_bf16_f32 v231, v129, v125
	v_cvt_pk_bf16_f32 v235, v128, v124
	s_nop 0
	v_mfma_f32_16x16x32_bf16 v[120:123], v[208:211], v[228:231], v[148:151]
	v_mfma_f32_16x16x32_bf16 v[104:107], v[208:211], v[232:235], v[108:111]
	v_mfma_f32_16x16x32_bf16 v[116:119], v[212:215], v[228:231], v[216:219]
	v_mfma_f32_16x16x32_bf16 v[100:103], v[212:215], v[232:235], v[100:103]
	s_waitcnt lgkmcnt(2)
	v_mfma_f32_16x16x32_bf16 v[112:115], v[136:139], v[228:231], v[204:207]
	v_mfma_f32_16x16x32_bf16 v[96:99], v[136:139], v[232:235], v[144:147]
	s_waitcnt lgkmcnt(1)
	v_mfma_f32_16x16x32_bf16 v[108:111], v[220:223], v[228:231], v[224:227]
	v_mfma_f32_16x16x32_bf16 v[92:95], v[220:223], v[232:235], v[92:95]
	s_and_saveexec_b64 s[48:49], s[10:11]
	ds_write_b128 v199, v[36:39] offset:12288
	s_or_b64 exec, exec, s[48:49]
	v_pk_add_f32 v[126:127], v[152:153], 0 op_sel_hi:[1,0]
	v_pk_add_f32 v[130:131], v[154:155], 0 op_sel_hi:[1,0]
	v_pk_add_f32 v[136:137], v[180:181], 0 op_sel_hi:[1,0]
	v_pk_add_f32 v[138:139], v[184:185], 0 op_sel_hi:[1,0]
	v_pk_add_f32 v[126:127], v[192:193], v[126:127]
	v_pk_add_f32 v[130:131], v[190:191], v[130:131]
	v_pk_add_f32 v[136:137], v[188:189], v[136:137]
	v_pk_add_f32 v[138:139], v[186:187], v[138:139]
	v_pk_add_f32 v[126:127], v[182:183], v[126:127]
	v_pk_add_f32 v[130:131], v[194:195], v[130:131]
	v_pk_add_f32 v[136:137], v[140:141], v[136:137]
	v_pk_add_f32 v[138:139], v[142:143], v[138:139]
	v_pk_add_f32 v[126:127], v[132:133], v[126:127]
	v_pk_add_f32 v[130:131], v[134:135], v[130:131]
	v_pk_add_f32 v[128:129], v[128:129], v[136:137]
	v_pk_add_f32 v[124:125], v[124:125], v[138:139]
	v_pk_add_f32 v[126:127], v[126:127], v[130:131]
	v_pk_add_f32 v[124:125], v[128:129], v[124:125]
	s_and_b32 s26, s9, 7
	v_pk_add_f32 v[124:125], v[126:127], v[124:125]
	s_waitcnt vmcnt(2)
	ds_write2_b64 v177, v[40:41], v[42:43] offset1:32
	v_pk_add_f32 v[184:185], v[2:3], v[124:125]
	v_lshl_add_u32 v2, s26, 6, v160
	s_lshl_b32 s26, s26, 7
	v_ashrrev_i32_e32 v3, 31, v2
	s_add_u32 s16, s28, s16
	v_lshlrev_b64 v[2:3], 17, v[2:3]
	s_addc_u32 s17, s29, s17
	v_lshl_add_u64 v[2:3], s[16:17], 0, v[2:3]
	s_lshl_b64 s[16:17], s[14:15], 19
	s_lshl_b64 s[14:15], s[14:15], 23
	s_or_b32 s14, s14, s26
	v_lshl_add_u64 v[180:181], v[170:171], 0, s[16:17]
	v_lshl_add_u64 v[182:183], v[172:173], 0, s[14:15]
	s_mov_b32 s26, 2
	s_waitcnt lgkmcnt(0)
	s_barrier
	s_branch .LBB0_887

.LBB0_895:
	ds_read_b128 v[124:127], v201 offset:12288
	ds_read_b128 v[128:131], v201 offset:13312
	ds_read_b128 v[136:139], v201 offset:15360
	ds_read_b128 v[140:143], v201 offset:14336
	ds_read_b128 v[148:151], v201 offset:18432
	ds_read_b128 v[152:155], v201 offset:19456
	ds_read_b128 v[204:207], v201 offset:21504
	ds_read_b128 v[208:211], v201 offset:20480
	s_waitcnt lgkmcnt(7)
	v_mfma_f32_16x16x32_bf16 v[132:135], v[124:127], v[12:15], v[44:47]
	v_exp_f32_e32 v195, v84
	v_exp_f32_e32 v194, v88
	v_exp_f32_e32 v88, v91
	v_mfma_f32_16x16x32_bf16 v[124:127], v[124:127], v[16:19], v[48:51]
	v_exp_f32_e32 v84, v81
	v_exp_f32_e32 v81, v78
	v_exp_f32_e32 v79, v79
	s_waitcnt lgkmcnt(3)
	v_mfma_f32_16x16x32_bf16 v[190:193], v[148:151], v[12:15], v[44:47]
	v_exp_f32_e32 v78, v83
	v_exp_f32_e32 v61, v61
	v_exp_f32_e32 v63, v63
	v_mfma_f32_16x16x32_bf16 v[148:151], v[148:151], v[16:19], v[48:51]
	v_exp_f32_e32 v83, v64
	v_exp_f32_e32 v64, v74
	v_exp_f32_e32 v67, v67
	v_mfma_f32_16x16x32_bf16 v[144:147], v[136:139], v[12:15], v[44:47]
	s_andn2_b64 vcc, exec, s[16:17]
	v_mfma_f32_16x16x32_bf16 v[136:139], v[136:139], v[16:19], v[48:51]
	s_waitcnt lgkmcnt(1)
	v_mfma_f32_16x16x32_bf16 v[212:215], v[204:207], v[12:15], v[44:47]
	v_mfma_f32_16x16x32_bf16 v[204:207], v[204:207], v[16:19], v[48:51]
	v_mfma_f32_16x16x32_bf16 v[132:135], v[128:131], v[4:7], v[132:135]
	v_mfma_f32_16x16x32_bf16 v[124:127], v[128:131], v[20:23], v[124:127]
	ds_read_b128 v[128:131], v201 offset:16384
	ds_read_b128 v[216:219], v201 offset:17408
	v_mfma_f32_16x16x32_bf16 v[220:223], v[152:155], v[20:23], v[148:151]
	s_nop 2
	ds_read_b128 v[148:151], v201 offset:22528
	ds_read_b128 v[224:227], v201 offset:23552
	s_waitcnt lgkmcnt(3)
	v_mfma_f32_16x16x32_bf16 v[144:147], v[128:131], v[4:7], v[144:147]
	v_mfma_f32_16x16x32_bf16 v[128:131], v[128:131], v[20:23], v[136:139]
	s_waitcnt lgkmcnt(1)
	v_mfma_f32_16x16x32_bf16 v[204:207], v[148:151], v[20:23], v[204:207]
	v_mfma_f32_16x16x32_bf16 v[136:139], v[152:155], v[4:7], v[190:193]
	v_mfma_f32_16x16x32_bf16 v[212:215], v[148:151], v[4:7], v[212:215]
	s_nop 1
	v_exp_f32_e32 v193, v85
	v_exp_f32_e32 v192, v89
	v_exp_f32_e32 v191, v86
	v_mfma_f32_16x16x32_bf16 v[148:151], v[140:143], v[8:11], v[132:135]
	v_exp_f32_e32 v190, v90
	v_exp_f32_e32 v89, v87
	v_exp_f32_e32 v87, v76
	v_mfma_f32_16x16x32_bf16 v[152:155], v[140:143], v[24:27], v[124:127]
	v_exp_f32_e32 v86, v80
	v_exp_f32_e32 v85, v77
	v_exp_f32_e32 v80, v82
	v_mfma_f32_16x16x32_bf16 v[140:143], v[216:219], v[8:11], v[144:147]
	v_exp_f32_e32 v77, v60
	v_exp_f32_e32 v76, v68
	v_exp_f32_e32 v60, v69
	v_mfma_f32_16x16x32_bf16 v[144:147], v[216:219], v[24:27], v[128:131]
	v_exp_f32_e32 v69, v62
	v_exp_f32_e32 v68, v70
	v_exp_f32_e32 v62, v71
	s_waitcnt lgkmcnt(0)
	v_mfma_f32_16x16x32_bf16 v[128:131], v[224:227], v[24:27], v[204:207]
	v_exp_f32_e32 v82, v72
	v_exp_f32_e32 v71, v65
	v_exp_f32_e32 v70, v73
	ds_read_b128 v[204:207], v200 offset:24576
	v_mfma_f32_16x16x32_bf16 v[132:135], v[208:211], v[8:11], v[136:139]
	v_exp_f32_e32 v65, v66
	v_exp_f32_e32 v66, v75
	v_cvt_pk_bf16_f32 v90, v77, v61
	v_mfma_f32_16x16x32_bf16 v[136:139], v[208:211], v[24:27], v[220:223]
	v_cvt_pk_bf16_f32 v208, v195, v193
	v_cvt_pk_bf16_f32 v209, v191, v89
	v_cvt_pk_bf16_f32 v210, v87, v85
	v_mfma_f32_16x16x32_bf16 v[124:127], v[224:227], v[8:11], v[212:215]
	v_cvt_pk_bf16_f32 v211, v81, v79
	ds_read_b128 v[216:219], v200 offset:26624
	ds_read_b128 v[220:223], v200 offset:25600
	v_cvt_pk_bf16_f32 v212, v194, v192
	v_cvt_pk_bf16_f32 v213, v190, v88
	v_cvt_pk_bf16_f32 v214, v86, v84
	v_cvt_pk_bf16_f32 v215, v80, v78
	s_waitcnt lgkmcnt(2)
	v_mfma_f32_16x16x32_bf16 v[120:123], v[204:207], v[208:211], v[120:123]
	v_cvt_pk_bf16_f32 v91, v69, v63
	v_mfma_f32_16x16x32_bf16 v[104:107], v[204:207], v[212:215], v[104:107]
	ds_read_b128 v[204:207], v200 offset:28672
	ds_read_b128 v[224:227], v200 offset:27648
	s_waitcnt lgkmcnt(3)
	v_mfma_f32_16x16x32_bf16 v[228:231], v[216:219], v[208:211], v[116:119]
	v_mfma_f32_16x16x32_bf16 v[100:103], v[216:219], v[212:215], v[100:103]
	s_nop 1
	ds_read_b128 v[116:119], v200 offset:30720
	ds_read_b128 v[216:219], v200 offset:29696
	s_waitcnt lgkmcnt(3)
	v_mfma_f32_16x16x32_bf16 v[232:235], v[204:207], v[208:211], v[112:115]
	v_mfma_f32_16x16x32_bf16 v[96:99], v[204:207], v[212:215], v[96:99]
	ds_read_b128 v[204:207], v200 offset:31744
	s_waitcnt lgkmcnt(2)
	v_mfma_f32_16x16x32_bf16 v[208:211], v[116:119], v[208:211], v[108:111]
	v_mfma_f32_16x16x32_bf16 v[72:75], v[116:119], v[212:215], v[92:95]
	v_cvt_pk_bf16_f32 v212, v76, v60
	v_cvt_pk_bf16_f32 v213, v68, v62
	v_cvt_pk_bf16_f32 v214, v82, v70
	v_cvt_pk_bf16_f32 v92, v83, v71
	v_cvt_pk_bf16_f32 v93, v65, v67
	v_cvt_pk_bf16_f32 v215, v64, v66
	s_nop 0
	v_mfma_f32_16x16x32_bf16 v[120:123], v[220:223], v[90:93], v[120:123]
	v_mfma_f32_16x16x32_bf16 v[116:119], v[220:223], v[212:215], v[104:107]
	v_mfma_f32_16x16x32_bf16 v[112:115], v[224:227], v[90:93], v[228:231]
	v_mfma_f32_16x16x32_bf16 v[108:111], v[224:227], v[212:215], v[100:103]
	s_waitcnt lgkmcnt(1)
	v_mfma_f32_16x16x32_bf16 v[104:107], v[216:219], v[90:93], v[232:235]
	v_mfma_f32_16x16x32_bf16 v[100:103], v[216:219], v[212:215], v[96:99]
	s_waitcnt lgkmcnt(0)
	v_mfma_f32_16x16x32_bf16 v[92:95], v[204:207], v[90:93], v[208:211]
	v_cndmask_b32_e64 v90, 0, 1, s[16:17]
	v_cmp_ne_u32_e64 s[14:15], 1, v90
	v_mfma_f32_16x16x32_bf16 v[96:99], v[204:207], v[212:215], v[72:75]
	s_cbranch_vccnz .LBB0_899
	s_waitcnt vmcnt(0)
	ds_write_b128 v197, v[52:55]
	s_and_saveexec_b64 s[16:17], s[10:11]
	ds_write_b128 v199, v[28:31]
	s_or_b64 exec, exec, s[16:17]
.LBB0_899:
	s_cmpk_gt_u32 s26, 0x7b
	s_waitcnt vmcnt(0)
	ds_write2_b64 v1, v[56:57], v[58:59] offset1:32
	s_waitcnt lgkmcnt(0)
	s_barrier
	s_cbranch_scc1 .LBB0_903
	v_add_co_u32_e32 v52, vcc, 0x2cd20000, v186
	s_nop 1
	v_addc_co_u32_e32 v53, vcc, 0, v187, vcc
	global_load_dwordx4 v[52:55], v[52:53], off
	s_and_saveexec_b64 s[16:17], s[10:11]
	s_cbranch_execz .LBB0_902
	global_load_dwordx4 v[28:31], v[180:181], off

.LBB0_907:
	ds_read_b128 v[60:63], v201
	ds_read_b128 v[64:67], v201 offset:1024
	ds_read_b128 v[72:75], v201 offset:3072
	ds_read_b128 v[76:79], v201 offset:2048
	ds_read_b128 v[84:87], v201 offset:6144
	ds_read_b128 v[88:91], v201 offset:7168
	ds_read_b128 v[190:193], v201 offset:9216
	ds_read_b128 v[204:207], v201 offset:8192
	s_waitcnt lgkmcnt(7)
	v_mfma_f32_16x16x32_bf16 v[68:71], v[60:63], v[12:15], v[44:47]
	v_exp_f32_e32 v149, v149
	v_exp_f32_e32 v151, v151
	v_exp_f32_e32 v143, v143
	v_mfma_f32_16x16x32_bf16 v[60:63], v[60:63], v[16:19], v[48:51]
	v_exp_f32_e32 v133, v133
	v_exp_f32_e32 v135, v135
	v_exp_f32_e32 v127, v127
	s_waitcnt lgkmcnt(3)
	v_mfma_f32_16x16x32_bf16 v[186:189], v[84:87], v[12:15], v[44:47]
	s_and_b64 vcc, exec, s[16:17]
	v_mfma_f32_16x16x32_bf16 v[84:87], v[84:87], v[16:19], v[48:51]
	v_mfma_f32_16x16x32_bf16 v[80:83], v[72:75], v[12:15], v[44:47]
	v_mfma_f32_16x16x32_bf16 v[72:75], v[72:75], v[16:19], v[48:51]
	s_waitcnt lgkmcnt(1)
	v_mfma_f32_16x16x32_bf16 v[208:211], v[190:193], v[12:15], v[44:47]
	v_mfma_f32_16x16x32_bf16 v[190:193], v[190:193], v[16:19], v[48:51]
	v_mfma_f32_16x16x32_bf16 v[68:71], v[64:67], v[4:7], v[68:71]
	v_mfma_f32_16x16x32_bf16 v[60:63], v[64:67], v[20:23], v[60:63]
	ds_read_b128 v[64:67], v201 offset:4096
	ds_read_b128 v[212:215], v201 offset:5120
	v_mfma_f32_16x16x32_bf16 v[216:219], v[88:91], v[20:23], v[84:87]
	s_nop 2
	ds_read_b128 v[84:87], v201 offset:10240
	ds_read_b128 v[220:223], v201 offset:11264
	s_waitcnt lgkmcnt(3)
	v_mfma_f32_16x16x32_bf16 v[80:83], v[64:67], v[4:7], v[80:83]
	v_mfma_f32_16x16x32_bf16 v[64:67], v[64:67], v[20:23], v[72:75]
	v_mfma_f32_16x16x32_bf16 v[72:75], v[88:91], v[4:7], v[186:189]
	s_waitcnt lgkmcnt(1)
	v_mfma_f32_16x16x32_bf16 v[188:191], v[84:87], v[20:23], v[190:193]
	s_nop 0
	v_exp_f32_e32 v187, v148
	v_exp_f32_e32 v186, v152
	v_exp_f32_e32 v148, v153
	v_mfma_f32_16x16x32_bf16 v[88:91], v[76:79], v[24:27], v[60:63]
	v_exp_f32_e32 v153, v150
	v_exp_f32_e32 v152, v154
	v_exp_f32_e32 v150, v155
	v_mfma_f32_16x16x32_bf16 v[60:63], v[204:207], v[8:11], v[72:75]
	v_exp_f32_e32 v155, v141
	v_exp_f32_e32 v154, v145
	v_exp_f32_e32 v145, v142
	s_waitcnt lgkmcnt(0)
	v_mfma_f32_16x16x32_bf16 v[72:75], v[220:223], v[24:27], v[188:191]
	v_exp_f32_e32 v142, v147
	v_exp_f32_e32 v141, v132
	v_exp_f32_e32 v132, v137
	ds_read_b128 v[190:193], v200 offset:32768
	v_mfma_f32_16x16x32_bf16 v[208:211], v[84:87], v[4:7], v[208:211]
	v_exp_f32_e32 v189, v140
	v_exp_f32_e32 v188, v144
	v_exp_f32_e32 v144, v146
	v_mfma_f32_16x16x32_bf16 v[84:87], v[76:79], v[8:11], v[68:71]
	v_exp_f32_e32 v140, v136
	v_exp_f32_e32 v137, v134
	v_exp_f32_e32 v136, v138
	v_mfma_f32_16x16x32_bf16 v[76:79], v[212:215], v[8:11], v[80:83]
	v_exp_f32_e32 v134, v139
	v_exp_f32_e32 v139, v124
	v_exp_f32_e32 v138, v128
	v_mfma_f32_16x16x32_bf16 v[80:83], v[212:215], v[24:27], v[64:67]
	v_exp_f32_e32 v147, v125
	v_exp_f32_e32 v146, v129
	v_exp_f32_e32 v125, v126
	v_mfma_f32_16x16x32_bf16 v[68:71], v[204:207], v[24:27], v[216:219]
	ds_read_b128 v[212:215], v200 offset:34816
	s_nop 1
	ds_read_b128 v[216:219], v200 offset:33792
	v_cvt_pk_bf16_f32 v204, v187, v149
	v_cvt_pk_bf16_f32 v205, v153, v151
	v_mfma_f32_16x16x32_bf16 v[64:67], v[220:223], v[8:11], v[208:211]
	v_cvt_pk_bf16_f32 v206, v189, v155
	v_cvt_pk_bf16_f32 v207, v145, v143
	v_exp_f32_e32 v124, v130
	v_cvt_pk_bf16_f32 v208, v186, v148
	v_cvt_pk_bf16_f32 v209, v152, v150
	v_cvt_pk_bf16_f32 v210, v188, v154
	v_cvt_pk_bf16_f32 v211, v144, v142
	s_waitcnt lgkmcnt(2)
	v_mfma_f32_16x16x32_bf16 v[120:123], v[190:193], v[204:207], v[120:123]
	v_exp_f32_e32 v126, v131
	v_mfma_f32_16x16x32_bf16 v[116:119], v[190:193], v[208:211], v[116:119]
	ds_read_b128 v[190:193], v200 offset:36864
	ds_read_b128 v[220:223], v200 offset:35840
	s_waitcnt lgkmcnt(3)
	v_mfma_f32_16x16x32_bf16 v[112:115], v[212:215], v[204:207], v[112:115]
	v_mfma_f32_16x16x32_bf16 v[108:111], v[212:215], v[208:211], v[108:111]
	ds_read_b128 v[212:215], v200 offset:38912
	ds_read_b128 v[224:227], v200 offset:37888
	ds_read_b128 v[232:235], v200 offset:39936
	s_waitcnt lgkmcnt(4)
	v_mfma_f32_16x16x32_bf16 v[228:231], v[190:193], v[204:207], v[104:107]
	v_mfma_f32_16x16x32_bf16 v[190:193], v[190:193], v[208:211], v[100:103]
	s_waitcnt lgkmcnt(2)
	v_mfma_f32_16x16x32_bf16 v[92:95], v[212:215], v[204:207], v[92:95]
	v_cvt_pk_bf16_f32 v204, v141, v133
	v_cvt_pk_bf16_f32 v205, v137, v135
	v_cvt_pk_bf16_f32 v206, v139, v147
	v_mfma_f32_16x16x32_bf16 v[128:131], v[212:215], v[208:211], v[96:99]
	v_cvt_pk_bf16_f32 v207, v125, v127
	v_cvt_pk_bf16_f32 v208, v140, v132
	v_cvt_pk_bf16_f32 v209, v136, v134
	v_cvt_pk_bf16_f32 v210, v138, v146
	v_cvt_pk_bf16_f32 v211, v124, v126
	v_mfma_f32_16x16x32_bf16 v[120:123], v[216:219], v[204:207], v[120:123]
	s_nop 0
	v_mfma_f32_16x16x32_bf16 v[104:107], v[216:219], v[208:211], v[116:119]
	v_mfma_f32_16x16x32_bf16 v[116:119], v[220:223], v[204:207], v[112:115]
	v_mfma_f32_16x16x32_bf16 v[100:103], v[220:223], v[208:211], v[108:111]
	s_waitcnt lgkmcnt(1)
	v_mfma_f32_16x16x32_bf16 v[112:115], v[224:227], v[204:207], v[228:231]
	v_mfma_f32_16x16x32_bf16 v[96:99], v[224:227], v[208:211], v[190:193]
	s_waitcnt lgkmcnt(0)
	v_mfma_f32_16x16x32_bf16 v[108:111], v[232:235], v[204:207], v[92:95]
	v_mfma_f32_16x16x32_bf16 v[92:95], v[232:235], v[208:211], v[128:131]
	s_cbranch_vccnz .LBB0_911
	ds_write_b128 v197, v[32:35] offset:12288
	s_and_saveexec_b64 s[16:17], s[10:11]
	ds_write_b128 v199, v[36:39] offset:12288
	s_or_b64 exec, exec, s[16:17]
.LBB0_911:
	s_and_b64 vcc, exec, s[14:15]
	s_cbranch_vccnz .LBB0_886
	ds_write2_b64 v177, v[40:41], v[42:43] offset1:32
	s_branch .LBB0_886
